# modulate_rows loop body hand-written: all 52 loads of a pass issued up front, counted vmcnt, interleaved 4-row wave reductions, stores never waited on
# speedup vs baseline: 1.0125x; 1.0020x over previous
; DI void modulate_rows(const float* x, const float* gain, const float* modl, int slot, bf16_t* U, int gw, int NGW, int lane) {
;     ...
;     for (int m0 = gw; m0 < MT; m0 += NR * NGW) {
;         int mr[NR]; f32x4 v[NR][4]; float s[NR];
; #pragma unroll
;         for (int q = 0; q < NR; ++q) { mr[q] = (m0 + q * NGW < MT) ? m0 + q * NGW : m0;
; #pragma unroll
;             for (int j = 0; j < 4; ++j) v[q][j] = ((const f32x4*)(x + (size_t)mr[q] * DM) + lane)[64 * j]; }
; #pragma unroll
;         for (int q = 0; q < NR; ++q) { float a = 0.f;
; #pragma unroll
;             for (int j = 0; j < 4; ++j) a += (v[q][j][0] * v[q][j][0] + v[q][j][1] * v[q][j][1]) + (v[q][j][2] * v[q][j][2] + v[q][j][3] * v[q][j][3]);
;             s[q] = rsqrtf(wave_sum(a) * (1.f / DM) + EPSF); }
.LBB0_998:
	global_load_dwordx4 v[0:3], v[74:75], off offset:-3072
	global_load_dwordx4 v[4:7], v[74:75], off offset:-2048
	global_load_dwordx4 v[8:11], v[74:75], off offset:-1024
	global_load_dwordx4 v[12:15], v[74:75], off
	v_add_u32_e32 v88, s95, v64
	v_add_u32_e32 v89, s36, v64
	s_mul_i32 s4, s72, 24
	v_add_u32_e32 v90, s4, v64
	v_cmp_gt_i32_e32 vcc, s85, v88
	v_ashrrev_i32_e32 v112, 11, v64
	v_mul_i32_i24_e32 v112, 0x9000, v112
	v_cndmask_b32_e32 v88, v64, v88, vcc
	v_cmp_gt_i32_e32 vcc, s85, v89
	v_add_u32_e32 v112, v112, v164
	v_add_u32_e32 v202, 0x1000, v112
	v_cndmask_b32_e32 v89, v64, v89, vcc
	v_cmp_gt_i32_e32 vcc, s85, v90
	v_lshlrev_b32_e32 v92, 12, v88
	v_add_u32_e32 v92, v92, v164
	v_cndmask_b32_e32 v90, v64, v90, vcc
	v_lshlrev_b32_e32 v110, 12, v89
	v_add_u32_e32 v110, v110, v164
	v_lshlrev_b32_e32 v111, 12, v90
	v_add_u32_e32 v111, v111, v164
	global_load_dwordx4 v[16:19], v92, s[18:19]
	global_load_dwordx4 v[20:23], v92, s[18:19] offset:1024
	global_load_dwordx4 v[24:27], v92, s[18:19] offset:2048
	global_load_dwordx4 v[28:31], v92, s[18:19] offset:3072
	global_load_dwordx4 v[32:35], v110, s[18:19]
	global_load_dwordx4 v[36:39], v110, s[18:19] offset:1024
	global_load_dwordx4 v[40:43], v110, s[18:19] offset:2048
	global_load_dwordx4 v[44:47], v110, s[18:19] offset:3072
	global_load_dwordx4 v[48:51], v111, s[18:19]
	global_load_dwordx4 v[52:55], v111, s[18:19] offset:1024
	global_load_dwordx4 v[56:59], v111, s[18:19] offset:2048
	global_load_dwordx4 v[60:63], v111, s[18:19] offset:3072
	global_load_dwordx4 v[76:79], v[70:71], off
	global_load_dwordx4 v[80:83], v[70:71], off offset:1024
	global_load_dwordx4 v[84:87], v[70:71], off offset:2048
	global_load_dwordx4 v[94:97], v[70:71], off offset:3072
	v_ashrrev_i32_e32 v113, 11, v88
	v_mul_i32_i24_e32 v113, 0x9000, v113
	v_add_u32_e32 v113, v113, v164
	v_add_u32_e32 v203, 0x1000, v113
	v_ashrrev_i32_e32 v162, 11, v89
	v_mul_i32_i24_e32 v162, 0x9000, v162
	v_add_u32_e32 v162, v162, v164
	v_add_u32_e32 v208, 0x1000, v162
	v_ashrrev_i32_e32 v163, 11, v90
	v_mul_i32_i24_e32 v163, 0x9000, v163
	v_add_u32_e32 v163, v163, v164
	v_add_u32_e32 v209, 0x1000, v163
	global_load_dwordx4 v[118:121], v202, s[6:7]
	global_load_dwordx4 v[170:173], v112, s[6:7]
	global_load_dwordx4 v[122:125], v203, s[6:7]
	global_load_dwordx4 v[174:177], v113, s[6:7]
	global_load_dwordx4 v[126:129], v208, s[6:7]
	global_load_dwordx4 v[178:181], v162, s[6:7]
	global_load_dwordx4 v[130:133], v209, s[6:7]
	global_load_dwordx4 v[182:185], v163, s[6:7]
	global_load_dwordx4 v[134:137], v202, s[6:7] offset:1024
	global_load_dwordx4 v[186:189], v112, s[6:7] offset:1024
	global_load_dwordx4 v[138:141], v203, s[6:7] offset:1024
	global_load_dwordx4 v[190:193], v113, s[6:7] offset:1024
	global_load_dwordx4 v[142:145], v208, s[6:7] offset:1024
	global_load_dwordx4 v[194:197], v162, s[6:7] offset:1024
	global_load_dwordx4 v[146:149], v209, s[6:7] offset:1024
	global_load_dwordx4 v[198:201], v163, s[6:7] offset:1024
	global_load_dwordx4 v[150:153], v202, s[6:7] offset:2048
	global_load_dwordx4 v[212:215], v112, s[6:7] offset:2048
	global_load_dwordx4 v[154:157], v203, s[6:7] offset:2048
	global_load_dwordx4 v[216:219], v113, s[6:7] offset:2048
	global_load_dwordx4 v[158:161], v208, s[6:7] offset:2048
	global_load_dwordx4 v[220:223], v162, s[6:7] offset:2048
	global_load_dwordx4 v[98:101], v209, s[6:7] offset:2048
	global_load_dwordx4 v[224:227], v163, s[6:7] offset:2048
	global_load_dwordx4 v[102:105], v202, s[6:7] offset:3072
	global_load_dwordx4 v[228:231], v112, s[6:7] offset:3072
	global_load_dwordx4 v[244:247], v203, s[6:7] offset:3072
	global_load_dwordx4 v[232:235], v113, s[6:7] offset:3072
	global_load_dwordx4 v[248:251], v208, s[6:7] offset:3072
	global_load_dwordx4 v[236:239], v162, s[6:7] offset:3072
	global_load_dwordx4 v[106:109], v209, s[6:7] offset:3072
	global_load_dwordx4 v[240:243], v163, s[6:7] offset:3072
	v_lshrrev_b32_e32 v253, 1, v164
	v_add_u32_e32 v253, 0x1980000, v253
	v_lshl_add_u32 v92, v88, 11, v253
	v_lshl_add_u32 v88, v89, 11, v253
	v_lshl_add_u32 v89, v90, 11, v253
	v_add_u32_e32 v64, s14, v64
	v_lshl_add_u64 v[74:75], v[74:75], 0, s[22:23]
	s_waitcnt vmcnt(36)
	v_pk_mul_f32 v[110:111], v[0:1], v[0:1]
	v_pk_fma_f32 v[110:111], v[2:3], v[2:3], v[110:111]
	v_pk_fma_f32 v[110:111], v[4:5], v[4:5], v[110:111]
	v_pk_fma_f32 v[110:111], v[6:7], v[6:7], v[110:111]
	v_pk_fma_f32 v[110:111], v[8:9], v[8:9], v[110:111]
	v_pk_fma_f32 v[110:111], v[10:11], v[10:11], v[110:111]
	v_pk_fma_f32 v[110:111], v[12:13], v[12:13], v[110:111]
	v_pk_fma_f32 v[110:111], v[14:15], v[14:15], v[110:111]
	v_pk_mul_f32 v[112:113], v[16:17], v[16:17]
	v_pk_fma_f32 v[112:113], v[18:19], v[18:19], v[112:113]
	v_pk_fma_f32 v[112:113], v[20:21], v[20:21], v[112:113]
	v_pk_fma_f32 v[112:113], v[22:23], v[22:23], v[112:113]
	v_pk_fma_f32 v[112:113], v[24:25], v[24:25], v[112:113]
	v_pk_fma_f32 v[112:113], v[26:27], v[26:27], v[112:113]
	v_pk_fma_f32 v[112:113], v[28:29], v[28:29], v[112:113]
	v_pk_fma_f32 v[112:113], v[30:31], v[30:31], v[112:113]
	v_pk_mul_f32 v[162:163], v[32:33], v[32:33]
	v_pk_fma_f32 v[162:163], v[34:35], v[34:35], v[162:163]
	v_pk_fma_f32 v[162:163], v[36:37], v[36:37], v[162:163]
	v_pk_fma_f32 v[162:163], v[38:39], v[38:39], v[162:163]
	v_pk_fma_f32 v[162:163], v[40:41], v[40:41], v[162:163]
	v_pk_fma_f32 v[162:163], v[42:43], v[42:43], v[162:163]
	v_pk_fma_f32 v[162:163], v[44:45], v[44:45], v[162:163]
	v_pk_fma_f32 v[162:163], v[46:47], v[46:47], v[162:163]
	v_pk_mul_f32 v[202:203], v[48:49], v[48:49]
	v_pk_fma_f32 v[202:203], v[50:51], v[50:51], v[202:203]
	v_pk_fma_f32 v[202:203], v[52:53], v[52:53], v[202:203]
	v_pk_fma_f32 v[202:203], v[54:55], v[54:55], v[202:203]
	v_pk_fma_f32 v[202:203], v[56:57], v[56:57], v[202:203]
	v_pk_fma_f32 v[202:203], v[58:59], v[58:59], v[202:203]
	v_pk_fma_f32 v[202:203], v[60:61], v[60:61], v[202:203]
	v_pk_fma_f32 v[202:203], v[62:63], v[62:63], v[202:203]
	v_add_f32_e32 v110, v110, v111
	v_add_f32_e32 v112, v112, v113
	v_add_f32_e32 v162, v162, v163
	v_add_f32_e32 v202, v202, v203
	ds_bpermute_b32 v208, v91, v110
	ds_bpermute_b32 v209, v91, v112
	ds_bpermute_b32 v252, v91, v162
	ds_bpermute_b32 v253, v91, v202
	s_waitcnt lgkmcnt(0)
; DI unsigned pk2(float lo, float hi) { f32x2_t v = {lo, hi}; bf16x2_t b = __builtin_convertvector(v, bf16x2_t); return __builtin_bit_cast(unsigned, b); }
; DI void modulate_rows(const float* x, const float* gain, const float* modl, int slot, bf16_t* U, int gw, int NGW, int lane) {
;     ...
;         for (int q = 0; q < NR; ++q) { float a = 0.f;
; #pragma unroll
;             for (int j = 0; j < 4; ++j) a += (v[q][j][0] * v[q][j][0] + v[q][j][1] * v[q][j][1]) + (v[q][j][2] * v[q][j][2] + v[q][j][3] * v[q][j][3]);
;             s[q] = rsqrtf(wave_sum(a) * (1.f / DM) + EPSF); }
; #pragma unroll
;         for (int j = 0; j < 4; ++j) { const int d = 4 * lane + 256 * j; const f32x4 g = *(const f32x4*)(gain + d);
; #pragma unroll
;             for (int q = 0; q < NR; ++q) { const float* mb = modl + (size_t)(mr[q] >> 11) * NMODW + slot * 3 * DM;
;                 const f32x4 y = v[q][j] * s[q] * g * (*(const f32x4*)(mb + DM + d) + 1.f) + *(const f32x4*)(mb + d);
;                 ((unsigned long long*)(U + (size_t)mr[q] * DM) + lane)[64 * j] = (unsigned long long)pk2(y[0], y[1]) | ((unsigned long long)pk2(y[2], y[3]) << 32); } }
	v_add_f32_e32 v110, v110, v208
	v_add_f32_e32 v112, v112, v209
	v_add_f32_e32 v162, v162, v252
	v_add_f32_e32 v202, v202, v253
	ds_bpermute_b32 v208, v93, v110
	ds_bpermute_b32 v209, v93, v112
	ds_bpermute_b32 v252, v93, v162
	ds_bpermute_b32 v253, v93, v202
	s_waitcnt lgkmcnt(0)
	v_add_f32_e32 v110, v110, v208
	v_add_f32_e32 v112, v112, v209
	v_add_f32_e32 v162, v162, v252
	v_add_f32_e32 v202, v202, v253
	ds_bpermute_b32 v208, v114, v110
	ds_bpermute_b32 v209, v114, v112
	ds_bpermute_b32 v252, v114, v162
	ds_bpermute_b32 v253, v114, v202
	s_waitcnt lgkmcnt(0)
	v_add_f32_e32 v110, v110, v208
	v_add_f32_e32 v112, v112, v209
	v_add_f32_e32 v162, v162, v252
	v_add_f32_e32 v202, v202, v253
	ds_bpermute_b32 v208, v115, v110
	ds_bpermute_b32 v209, v115, v112
	ds_bpermute_b32 v252, v115, v162
	ds_bpermute_b32 v253, v115, v202
	s_waitcnt lgkmcnt(0)
	v_add_f32_e32 v110, v110, v208
	v_add_f32_e32 v112, v112, v209
	v_add_f32_e32 v162, v162, v252
	v_add_f32_e32 v202, v202, v253
	ds_bpermute_b32 v208, v116, v110
	ds_bpermute_b32 v209, v116, v112
	ds_bpermute_b32 v252, v116, v162
	ds_bpermute_b32 v253, v116, v202
	s_waitcnt lgkmcnt(0)
	v_add_f32_e32 v110, v110, v208
	v_add_f32_e32 v112, v112, v209
	v_add_f32_e32 v162, v162, v252
	v_add_f32_e32 v202, v202, v253
	ds_bpermute_b32 v208, v117, v110
	ds_bpermute_b32 v209, v117, v112
	ds_bpermute_b32 v252, v117, v162
	ds_bpermute_b32 v253, v117, v202
	s_waitcnt lgkmcnt(0)
	v_add_f32_e32 v110, v110, v208
	v_add_f32_e32 v112, v112, v209
	v_add_f32_e32 v162, v162, v252
	v_add_f32_e32 v202, v202, v253
	v_fma_f32 v110, v110, s24, v169
	v_fma_f32 v112, v112, s24, v169
	v_fma_f32 v162, v162, s24, v169
	v_fma_f32 v202, v202, s24, v169
	v_mul_f32_e32 v208, 0x4b800000, v110
	v_mul_f32_e32 v209, 0x4b800000, v112
	v_mul_f32_e32 v252, 0x4b800000, v162
	v_mul_f32_e32 v253, 0x4b800000, v202
	v_cmp_gt_f32_e32 vcc, s57, v110
	s_nop 1
	v_cndmask_b32_e32 v110, v110, v208, vcc
	v_rsq_f32_e32 v110, v110
	s_nop 0
	v_mul_f32_e32 v208, 0x45800000, v110
	v_cndmask_b32_e32 v110, v110, v208, vcc
	v_cmp_gt_f32_e32 vcc, s57, v112
	s_nop 1
	v_cndmask_b32_e32 v112, v112, v209, vcc
	v_rsq_f32_e32 v112, v112
	s_nop 0
	v_mul_f32_e32 v209, 0x45800000, v112
	v_cndmask_b32_e32 v112, v112, v209, vcc
	v_cmp_gt_f32_e32 vcc, s57, v162
	s_nop 1
	v_cndmask_b32_e32 v162, v162, v252, vcc
	v_rsq_f32_e32 v162, v162
	s_nop 0
	v_mul_f32_e32 v252, 0x45800000, v162
	v_cndmask_b32_e32 v162, v162, v252, vcc
	v_cmp_gt_f32_e32 vcc, s57, v202
	s_nop 1
	v_cndmask_b32_e32 v202, v202, v253, vcc
	v_rsq_f32_e32 v202, v202
	s_nop 0
	v_mul_f32_e32 v253, 0x45800000, v202
	v_cndmask_b32_e32 v202, v202, v253, vcc
	s_waitcnt vmcnt(30)
	v_pk_mul_f32 v[0:1], v[0:1], v[110:111] op_sel_hi:[1,0]
	v_pk_mul_f32 v[2:3], v[2:3], v[110:111] op_sel_hi:[1,0]
	v_pk_add_f32 v[118:119], v[118:119], 1.0 op_sel_hi:[1,0]
	v_pk_add_f32 v[120:121], v[120:121], 1.0 op_sel_hi:[1,0]
	v_pk_mul_f32 v[0:1], v[0:1], v[76:77]
	v_pk_mul_f32 v[2:3], v[2:3], v[78:79]
	v_pk_fma_f32 v[0:1], v[0:1], v[118:119], v[170:171]
	v_pk_fma_f32 v[2:3], v[2:3], v[120:121], v[172:173]
	v_cvt_pk_bf16_f32 v0, v0, v1
	v_cvt_pk_bf16_f32 v1, v2, v3
	global_store_dwordx2 v[72:73], v[0:1], off offset:-1536
	s_waitcnt vmcnt(29)
	v_pk_mul_f32 v[16:17], v[16:17], v[112:113] op_sel_hi:[1,0]
	v_pk_mul_f32 v[18:19], v[18:19], v[112:113] op_sel_hi:[1,0]
	v_pk_add_f32 v[122:123], v[122:123], 1.0 op_sel_hi:[1,0]
	v_pk_add_f32 v[124:125], v[124:125], 1.0 op_sel_hi:[1,0]
	v_pk_mul_f32 v[16:17], v[16:17], v[76:77]
	v_pk_mul_f32 v[18:19], v[18:19], v[78:79]
	v_pk_fma_f32 v[16:17], v[16:17], v[122:123], v[174:175]
	v_pk_fma_f32 v[18:19], v[18:19], v[124:125], v[176:177]
	v_cvt_pk_bf16_f32 v16, v16, v17
	v_cvt_pk_bf16_f32 v17, v18, v19
	global_store_dwordx2 v92, v[16:17], s[96:97]
	s_waitcnt vmcnt(28)
	v_pk_mul_f32 v[32:33], v[32:33], v[162:163] op_sel_hi:[1,0]
	v_pk_mul_f32 v[34:35], v[34:35], v[162:163] op_sel_hi:[1,0]
	v_pk_add_f32 v[126:127], v[126:127], 1.0 op_sel_hi:[1,0]
	v_pk_add_f32 v[128:129], v[128:129], 1.0 op_sel_hi:[1,0]
	v_pk_mul_f32 v[32:33], v[32:33], v[76:77]
	v_pk_mul_f32 v[34:35], v[34:35], v[78:79]
	v_pk_fma_f32 v[32:33], v[32:33], v[126:127], v[178:179]
	v_pk_fma_f32 v[34:35], v[34:35], v[128:129], v[180:181]
	v_cvt_pk_bf16_f32 v32, v32, v33
	v_cvt_pk_bf16_f32 v33, v34, v35
	global_store_dwordx2 v88, v[32:33], s[96:97]
	s_waitcnt vmcnt(27)
	v_pk_mul_f32 v[48:49], v[48:49], v[202:203] op_sel_hi:[1,0]
	v_pk_mul_f32 v[50:51], v[50:51], v[202:203] op_sel_hi:[1,0]
	v_pk_add_f32 v[130:131], v[130:131], 1.0 op_sel_hi:[1,0]
	v_pk_add_f32 v[132:133], v[132:133], 1.0 op_sel_hi:[1,0]
	v_pk_mul_f32 v[48:49], v[48:49], v[76:77]
	v_pk_mul_f32 v[50:51], v[50:51], v[78:79]
	v_pk_fma_f32 v[48:49], v[48:49], v[130:131], v[182:183]
	v_pk_fma_f32 v[50:51], v[50:51], v[132:133], v[184:185]
	v_cvt_pk_bf16_f32 v48, v48, v49
	v_cvt_pk_bf16_f32 v49, v50, v51
	global_store_dwordx2 v89, v[48:49], s[96:97]
	s_waitcnt vmcnt(26)
	v_pk_mul_f32 v[4:5], v[4:5], v[110:111] op_sel_hi:[1,0]
	v_pk_mul_f32 v[6:7], v[6:7], v[110:111] op_sel_hi:[1,0]
	v_pk_add_f32 v[134:135], v[134:135], 1.0 op_sel_hi:[1,0]
	v_pk_add_f32 v[136:137], v[136:137], 1.0 op_sel_hi:[1,0]
	v_pk_mul_f32 v[4:5], v[4:5], v[80:81]
	v_pk_mul_f32 v[6:7], v[6:7], v[82:83]
	v_pk_fma_f32 v[4:5], v[4:5], v[134:135], v[186:187]
	v_pk_fma_f32 v[6:7], v[6:7], v[136:137], v[188:189]
	v_cvt_pk_bf16_f32 v4, v4, v5
	v_cvt_pk_bf16_f32 v5, v6, v7
	global_store_dwordx2 v[72:73], v[4:5], off offset:-1024
	s_waitcnt vmcnt(25)
; DI unsigned pk2(float lo, float hi) { f32x2_t v = {lo, hi}; bf16x2_t b = __builtin_convertvector(v, bf16x2_t); return __builtin_bit_cast(unsigned, b); }
; DI void modulate_rows(const float* x, const float* gain, const float* modl, int slot, bf16_t* U, int gw, int NGW, int lane) {
;     ...
;         for (int j = 0; j < 4; ++j) { const int d = 4 * lane + 256 * j; const f32x4 g = *(const f32x4*)(gain + d);
; #pragma unroll
;             for (int q = 0; q < NR; ++q) { const float* mb = modl + (size_t)(mr[q] >> 11) * NMODW + slot * 3 * DM;
;                 const f32x4 y = v[q][j] * s[q] * g * (*(const f32x4*)(mb + DM + d) + 1.f) + *(const f32x4*)(mb + d);
;                 ((unsigned long long*)(U + (size_t)mr[q] * DM) + lane)[64 * j] = (unsigned long long)pk2(y[0], y[1]) | ((unsigned long long)pk2(y[2], y[3]) << 32); } }
;     }
	v_pk_mul_f32 v[20:21], v[20:21], v[112:113] op_sel_hi:[1,0]
	v_pk_mul_f32 v[22:23], v[22:23], v[112:113] op_sel_hi:[1,0]
	v_pk_add_f32 v[138:139], v[138:139], 1.0 op_sel_hi:[1,0]
	v_pk_add_f32 v[140:141], v[140:141], 1.0 op_sel_hi:[1,0]
	v_pk_mul_f32 v[20:21], v[20:21], v[80:81]
	v_pk_mul_f32 v[22:23], v[22:23], v[82:83]
	v_pk_fma_f32 v[20:21], v[20:21], v[138:139], v[190:191]
	v_pk_fma_f32 v[22:23], v[22:23], v[140:141], v[192:193]
	v_cvt_pk_bf16_f32 v20, v20, v21
	v_cvt_pk_bf16_f32 v21, v22, v23
	global_store_dwordx2 v92, v[20:21], s[96:97] offset:512
	s_waitcnt vmcnt(24)
	v_pk_mul_f32 v[36:37], v[36:37], v[162:163] op_sel_hi:[1,0]
	v_pk_mul_f32 v[38:39], v[38:39], v[162:163] op_sel_hi:[1,0]
	v_pk_add_f32 v[142:143], v[142:143], 1.0 op_sel_hi:[1,0]
	v_pk_add_f32 v[144:145], v[144:145], 1.0 op_sel_hi:[1,0]
	v_pk_mul_f32 v[36:37], v[36:37], v[80:81]
	v_pk_mul_f32 v[38:39], v[38:39], v[82:83]
	v_pk_fma_f32 v[36:37], v[36:37], v[142:143], v[194:195]
	v_pk_fma_f32 v[38:39], v[38:39], v[144:145], v[196:197]
	v_cvt_pk_bf16_f32 v36, v36, v37
	v_cvt_pk_bf16_f32 v37, v38, v39
	global_store_dwordx2 v88, v[36:37], s[96:97] offset:512
	s_waitcnt vmcnt(23)
	v_pk_mul_f32 v[52:53], v[52:53], v[202:203] op_sel_hi:[1,0]
	v_pk_mul_f32 v[54:55], v[54:55], v[202:203] op_sel_hi:[1,0]
	v_pk_add_f32 v[146:147], v[146:147], 1.0 op_sel_hi:[1,0]
	v_pk_add_f32 v[148:149], v[148:149], 1.0 op_sel_hi:[1,0]
	v_pk_mul_f32 v[52:53], v[52:53], v[80:81]
	v_pk_mul_f32 v[54:55], v[54:55], v[82:83]
	v_pk_fma_f32 v[52:53], v[52:53], v[146:147], v[198:199]
	v_pk_fma_f32 v[54:55], v[54:55], v[148:149], v[200:201]
	v_cvt_pk_bf16_f32 v52, v52, v53
	v_cvt_pk_bf16_f32 v53, v54, v55
	global_store_dwordx2 v89, v[52:53], s[96:97] offset:512
	s_waitcnt vmcnt(22)
	v_pk_mul_f32 v[8:9], v[8:9], v[110:111] op_sel_hi:[1,0]
	v_pk_mul_f32 v[10:11], v[10:11], v[110:111] op_sel_hi:[1,0]
	v_pk_add_f32 v[150:151], v[150:151], 1.0 op_sel_hi:[1,0]
	v_pk_add_f32 v[152:153], v[152:153], 1.0 op_sel_hi:[1,0]
	v_pk_mul_f32 v[8:9], v[8:9], v[84:85]
	v_pk_mul_f32 v[10:11], v[10:11], v[86:87]
	v_pk_fma_f32 v[8:9], v[8:9], v[150:151], v[212:213]
	v_pk_fma_f32 v[10:11], v[10:11], v[152:153], v[214:215]
	v_cvt_pk_bf16_f32 v8, v8, v9
	v_cvt_pk_bf16_f32 v9, v10, v11
	global_store_dwordx2 v[72:73], v[8:9], off offset:-512
	s_waitcnt vmcnt(21)
	v_pk_mul_f32 v[24:25], v[24:25], v[112:113] op_sel_hi:[1,0]
	v_pk_mul_f32 v[26:27], v[26:27], v[112:113] op_sel_hi:[1,0]
	v_pk_add_f32 v[154:155], v[154:155], 1.0 op_sel_hi:[1,0]
	v_pk_add_f32 v[156:157], v[156:157], 1.0 op_sel_hi:[1,0]
	v_pk_mul_f32 v[24:25], v[24:25], v[84:85]
	v_pk_mul_f32 v[26:27], v[26:27], v[86:87]
	v_pk_fma_f32 v[24:25], v[24:25], v[154:155], v[216:217]
	v_pk_fma_f32 v[26:27], v[26:27], v[156:157], v[218:219]
	v_cvt_pk_bf16_f32 v24, v24, v25
	v_cvt_pk_bf16_f32 v25, v26, v27
	global_store_dwordx2 v92, v[24:25], s[96:97] offset:1024
	s_waitcnt vmcnt(20)
	v_pk_mul_f32 v[40:41], v[40:41], v[162:163] op_sel_hi:[1,0]
	v_pk_mul_f32 v[42:43], v[42:43], v[162:163] op_sel_hi:[1,0]
	v_pk_add_f32 v[158:159], v[158:159], 1.0 op_sel_hi:[1,0]
	v_pk_add_f32 v[160:161], v[160:161], 1.0 op_sel_hi:[1,0]
	v_pk_mul_f32 v[40:41], v[40:41], v[84:85]
	v_pk_mul_f32 v[42:43], v[42:43], v[86:87]
	v_pk_fma_f32 v[40:41], v[40:41], v[158:159], v[220:221]
	v_pk_fma_f32 v[42:43], v[42:43], v[160:161], v[222:223]
	v_cvt_pk_bf16_f32 v40, v40, v41
	v_cvt_pk_bf16_f32 v41, v42, v43
	global_store_dwordx2 v88, v[40:41], s[96:97] offset:1024
	s_waitcnt vmcnt(19)
	v_pk_mul_f32 v[56:57], v[56:57], v[202:203] op_sel_hi:[1,0]
	v_pk_mul_f32 v[58:59], v[58:59], v[202:203] op_sel_hi:[1,0]
	v_pk_add_f32 v[98:99], v[98:99], 1.0 op_sel_hi:[1,0]
	v_pk_add_f32 v[100:101], v[100:101], 1.0 op_sel_hi:[1,0]
	v_pk_mul_f32 v[56:57], v[56:57], v[84:85]
	v_pk_mul_f32 v[58:59], v[58:59], v[86:87]
	v_pk_fma_f32 v[56:57], v[56:57], v[98:99], v[224:225]
	v_pk_fma_f32 v[58:59], v[58:59], v[100:101], v[226:227]
	v_cvt_pk_bf16_f32 v56, v56, v57
	v_cvt_pk_bf16_f32 v57, v58, v59
	global_store_dwordx2 v89, v[56:57], s[96:97] offset:1024
	s_waitcnt vmcnt(18)
	v_pk_mul_f32 v[12:13], v[12:13], v[110:111] op_sel_hi:[1,0]
	v_pk_mul_f32 v[14:15], v[14:15], v[110:111] op_sel_hi:[1,0]
	v_pk_add_f32 v[102:103], v[102:103], 1.0 op_sel_hi:[1,0]
	v_pk_add_f32 v[104:105], v[104:105], 1.0 op_sel_hi:[1,0]
	v_pk_mul_f32 v[12:13], v[12:13], v[94:95]
	v_pk_mul_f32 v[14:15], v[14:15], v[96:97]
	v_pk_fma_f32 v[12:13], v[12:13], v[102:103], v[228:229]
	v_pk_fma_f32 v[14:15], v[14:15], v[104:105], v[230:231]
	v_cvt_pk_bf16_f32 v12, v12, v13
	v_cvt_pk_bf16_f32 v13, v14, v15
	global_store_dwordx2 v[72:73], v[12:13], off
	s_waitcnt vmcnt(17)
	v_pk_mul_f32 v[28:29], v[28:29], v[112:113] op_sel_hi:[1,0]
	v_pk_mul_f32 v[30:31], v[30:31], v[112:113] op_sel_hi:[1,0]
	v_pk_add_f32 v[244:245], v[244:245], 1.0 op_sel_hi:[1,0]
	v_pk_add_f32 v[246:247], v[246:247], 1.0 op_sel_hi:[1,0]
	v_pk_mul_f32 v[28:29], v[28:29], v[94:95]
	v_pk_mul_f32 v[30:31], v[30:31], v[96:97]
	v_pk_fma_f32 v[28:29], v[28:29], v[244:245], v[232:233]
	v_pk_fma_f32 v[30:31], v[30:31], v[246:247], v[234:235]
	v_cvt_pk_bf16_f32 v28, v28, v29
	v_cvt_pk_bf16_f32 v29, v30, v31
	global_store_dwordx2 v92, v[28:29], s[96:97] offset:1536
	s_waitcnt vmcnt(16)
	v_pk_mul_f32 v[44:45], v[44:45], v[162:163] op_sel_hi:[1,0]
	v_pk_mul_f32 v[46:47], v[46:47], v[162:163] op_sel_hi:[1,0]
	v_pk_add_f32 v[248:249], v[248:249], 1.0 op_sel_hi:[1,0]
	v_pk_add_f32 v[250:251], v[250:251], 1.0 op_sel_hi:[1,0]
	v_pk_mul_f32 v[44:45], v[44:45], v[94:95]
	v_pk_mul_f32 v[46:47], v[46:47], v[96:97]
	v_pk_fma_f32 v[44:45], v[44:45], v[248:249], v[236:237]
	v_pk_fma_f32 v[46:47], v[46:47], v[250:251], v[238:239]
	v_cvt_pk_bf16_f32 v44, v44, v45
	v_cvt_pk_bf16_f32 v45, v46, v47
	global_store_dwordx2 v88, v[44:45], s[96:97] offset:1536
	s_waitcnt vmcnt(15)
	v_pk_mul_f32 v[60:61], v[60:61], v[202:203] op_sel_hi:[1,0]
	v_pk_mul_f32 v[62:63], v[62:63], v[202:203] op_sel_hi:[1,0]
	v_pk_add_f32 v[106:107], v[106:107], 1.0 op_sel_hi:[1,0]
	v_pk_add_f32 v[108:109], v[108:109], 1.0 op_sel_hi:[1,0]
	v_pk_mul_f32 v[60:61], v[60:61], v[94:95]
	v_pk_mul_f32 v[62:63], v[62:63], v[96:97]
	v_pk_fma_f32 v[60:61], v[60:61], v[106:107], v[240:241]
	v_pk_fma_f32 v[62:63], v[62:63], v[108:109], v[242:243]
	v_cvt_pk_bf16_f32 v60, v60, v61
	v_cvt_pk_bf16_f32 v61, v62, v63
	global_store_dwordx2 v89, v[60:61], s[96:97] offset:1536
	v_cmp_lt_i32_e32 vcc, s81, v64
	s_or_b64 s[8:9], vcc, s[8:9]
	v_lshl_add_u64 v[72:73], v[72:73], 0, s[16:17]
	s_andn2_b64 exec, exec, s[8:9]
	s_cbranch_execnz .LBB0_998
